# WY producer solve: (q4==rr ? own : 0) - pre as one fma with a per-lane 1.0/0.0 mask register instead of v_cndmask + v_sub (60 fewer VALU per task wave, bit-identical)
# speedup vs baseline: 1.0017x; 1.0016x over previous
; #define WY_RDBLK(m_) do { _Pragma("unroll") for (int t_ = 0; t_ <= (m_); ++t_) LB[(m_) & 1][t_] = *(const LAS f32x4*)(lq + (m_) * WY_BS + 4 * t_); } while (0)
; __device__ __forceinline__ int wy_producer_task(const Ctx& c, int l, int tk, WyPre& P, unsigned* head) {
;     ...
;         for (int m = 0; m < 16; ++m) {
;             if (m + 1 < 16) WY_RDBLK(m + 1);
;             __builtin_amdgcn_sched_barrier(0);
;             f32x4 pre = (f32x4){0.f, 0.f, 0.f, 0.f};
; #pragma unroll
;             for (int t = 0; t < m; ++t) pre = LB[m & 1][t] * own[t] + pre;
; #pragma unroll
;             for (int rr = 0; rr < 4; ++rr) {
;                 float acc = ((q4 == rr) ? own[m] : 0.f) - pre[rr];
;                 if (rr > 0) acc = fmaf(-LB[m & 1][m][rr], own[m], acc);
;                 const float x = quad_sum(acc);
;                 own[m] = (q4 == rr) ? x : own[m]; }
;             __builtin_amdgcn_sched_barrier(0);
;         }
.LBB0_1086:
.LBB0_1087:
	s_movk_i32 s2, 0x110
	v_mad_u32_u24 v21, v0, s2, 0
	s_waitcnt lgkmcnt(0)
	s_barrier
	ds_read_b128 v[22:25], v21 offset:34304
	ds_read_b128 v[26:29], v21 offset:35392
	ds_read_b128 v[30:33], v21 offset:35408
	v_cmp_eq_u32_e64 s[6:7], 0, v0
	v_cmp_eq_u32_e32 vcc, 1, v0
	v_cmp_eq_u32_e64 s[2:3], 2, v0
	v_cndmask_b32_e64 v20, 0, v18, s[6:7]
	s_waitcnt lgkmcnt(2)
	v_cndmask_b32_e32 v22, 0, v18, vcc
	v_cmp_eq_u32_e64 s[4:5], 3, v0
	s_nop 1
	v_cndmask_b32_e64 v236, 0, 1.0, s[6:7]
	v_cndmask_b32_e64 v237, 0, 1.0, vcc
	v_cndmask_b32_e64 v238, 0, 1.0, s[2:3]
	v_cndmask_b32_e64 v239, 0, 1.0, s[4:5]
	v_add_f32_dpp v20, v20, v20 quad_perm:[1,0,3,2] row_mask:0xf bank_mask:0xf bound_ctrl:1
	s_nop 1
	v_add_f32_dpp v20, v20, v20 quad_perm:[2,3,0,1] row_mask:0xf bank_mask:0xf bound_ctrl:1
	v_cndmask_b32_e64 v20, v18, v20, s[6:7]
	v_fma_f32 v22, -v23, v20, v22
	s_nop 1
	v_add_f32_dpp v22, v22, v22 quad_perm:[1,0,3,2] row_mask:0xf bank_mask:0xf bound_ctrl:1
	s_nop 1
	v_add_f32_dpp v22, v22, v22 quad_perm:[2,3,0,1] row_mask:0xf bank_mask:0xf bound_ctrl:1
	v_cndmask_b32_e32 v20, v20, v22, vcc
	v_cndmask_b32_e64 v22, 0, v18, s[2:3]
	v_fma_f32 v22, -v24, v20, v22
	v_cndmask_b32_e64 v18, 0, v18, s[4:5]
	s_nop 0
	v_add_f32_dpp v22, v22, v22 quad_perm:[1,0,3,2] row_mask:0xf bank_mask:0xf bound_ctrl:1
	s_nop 1
	v_add_f32_dpp v22, v22, v22 quad_perm:[2,3,0,1] row_mask:0xf bank_mask:0xf bound_ctrl:1
	v_cndmask_b32_e64 v20, v20, v22, s[2:3]
	v_fma_f32 v18, -v25, v20, v18
	s_nop 1
	v_add_f32_dpp v18, v18, v18 quad_perm:[1,0,3,2] row_mask:0xf bank_mask:0xf bound_ctrl:1
	s_nop 1
	v_add_f32_dpp v18, v18, v18 quad_perm:[2,3,0,1] row_mask:0xf bank_mask:0xf bound_ctrl:1
	v_cndmask_b32_e64 v18, v20, v18, s[4:5]
	ds_read_b128 v[22:25], v21 offset:36480
	ds_read_b128 v[34:37], v21 offset:36496
	ds_read_b128 v[38:41], v21 offset:36512
	s_waitcnt lgkmcnt(4)
	v_pk_fma_f32 v[26:27], v[26:27], v[18:19], 0 op_sel_hi:[1,0,0]
	v_fma_f32 v20, v19, v236, -v26
	v_fma_f32 v26, v19, v237, -v27
	s_nop 0
	v_add_f32_dpp v20, v20, v20 quad_perm:[1,0,3,2] row_mask:0xf bank_mask:0xf bound_ctrl:1
	v_pk_fma_f32 v[28:29], v[28:29], v[18:19], 0 op_sel_hi:[1,0,0]
	s_nop 0
	v_add_f32_dpp v20, v20, v20 quad_perm:[2,3,0,1] row_mask:0xf bank_mask:0xf bound_ctrl:1
	v_cndmask_b32_e64 v20, v19, v20, s[6:7]
	s_waitcnt lgkmcnt(3)
	v_fma_f32 v26, -v31, v20, v26
	s_nop 1
	v_add_f32_dpp v26, v26, v26 quad_perm:[1,0,3,2] row_mask:0xf bank_mask:0xf bound_ctrl:1
	s_nop 1
	v_add_f32_dpp v26, v26, v26 quad_perm:[2,3,0,1] row_mask:0xf bank_mask:0xf bound_ctrl:1
	v_cndmask_b32_e32 v20, v20, v26, vcc
	v_fma_f32 v26, v19, v238, -v28
	v_fma_f32 v26, -v32, v20, v26
	v_fma_f32 v19, v19, v239, -v29
	s_nop 0
	v_add_f32_dpp v26, v26, v26 quad_perm:[1,0,3,2] row_mask:0xf bank_mask:0xf bound_ctrl:1
	s_nop 1
	v_add_f32_dpp v26, v26, v26 quad_perm:[2,3,0,1] row_mask:0xf bank_mask:0xf bound_ctrl:1
	v_cndmask_b32_e64 v20, v20, v26, s[2:3]
	v_fma_f32 v19, -v33, v20, v19
	s_nop 1
	v_add_f32_dpp v19, v19, v19 quad_perm:[1,0,3,2] row_mask:0xf bank_mask:0xf bound_ctrl:1
	s_nop 1
	v_add_f32_dpp v19, v19, v19 quad_perm:[2,3,0,1] row_mask:0xf bank_mask:0xf bound_ctrl:1
	v_cndmask_b32_e64 v20, v20, v19, s[4:5]
	ds_read_b128 v[26:29], v21 offset:37568
	ds_read_b128 v[30:33], v21 offset:37584
	ds_read_b128 v[42:45], v21 offset:37600
	ds_read_b128 v[46:49], v21 offset:37616
	s_waitcnt lgkmcnt(6)
	v_pk_fma_f32 v[22:23], v[22:23], v[18:19], 0 op_sel_hi:[1,0,0]
	v_pk_fma_f32 v[24:25], v[24:25], v[18:19], 0 op_sel_hi:[1,0,0]
	s_waitcnt lgkmcnt(5)
	v_pk_fma_f32 v[22:23], v[34:35], v[20:21], v[22:23] op_sel_hi:[1,0,1]
	v_fma_f32 v19, v16, v236, -v22
	v_fma_f32 v22, v16, v237, -v23
	s_nop 0
	v_add_f32_dpp v19, v19, v19 quad_perm:[1,0,3,2] row_mask:0xf bank_mask:0xf bound_ctrl:1
	v_pk_fma_f32 v[24:25], v[36:37], v[20:21], v[24:25] op_sel_hi:[1,0,1]
	s_nop 0
	v_add_f32_dpp v19, v19, v19 quad_perm:[2,3,0,1] row_mask:0xf bank_mask:0xf bound_ctrl:1
	v_cndmask_b32_e64 v19, v16, v19, s[6:7]
	s_waitcnt lgkmcnt(4)
	v_fma_f32 v22, -v39, v19, v22
	s_nop 1
	v_add_f32_dpp v22, v22, v22 quad_perm:[1,0,3,2] row_mask:0xf bank_mask:0xf bound_ctrl:1
	s_nop 1
	v_add_f32_dpp v22, v22, v22 quad_perm:[2,3,0,1] row_mask:0xf bank_mask:0xf bound_ctrl:1
	v_cndmask_b32_e32 v19, v19, v22, vcc
	v_fma_f32 v22, v16, v238, -v24
	v_fma_f32 v22, -v40, v19, v22
	v_fma_f32 v16, v16, v239, -v25
	s_nop 0
	v_add_f32_dpp v22, v22, v22 quad_perm:[1,0,3,2] row_mask:0xf bank_mask:0xf bound_ctrl:1
	s_nop 1
	v_add_f32_dpp v22, v22, v22 quad_perm:[2,3,0,1] row_mask:0xf bank_mask:0xf bound_ctrl:1
	v_cndmask_b32_e64 v19, v19, v22, s[2:3]
	v_fma_f32 v16, -v41, v19, v16
	s_nop 1
	v_add_f32_dpp v16, v16, v16 quad_perm:[1,0,3,2] row_mask:0xf bank_mask:0xf bound_ctrl:1
	s_nop 1
	v_add_f32_dpp v16, v16, v16 quad_perm:[2,3,0,1] row_mask:0xf bank_mask:0xf bound_ctrl:1
	v_cndmask_b32_e64 v16, v19, v16, s[4:5]
	ds_read_b128 v[34:37], v21 offset:38656
	ds_read_b128 v[38:41], v21 offset:38672
	ds_read_b128 v[50:53], v21 offset:38688
	ds_read_b128 v[54:57], v21 offset:38704
	ds_read_b128 v[22:25], v21 offset:38720
	s_waitcnt lgkmcnt(8)
	v_pk_fma_f32 v[26:27], v[18:19], v[26:27], 0 op_sel_hi:[0,1,0]
	s_waitcnt lgkmcnt(7)
	v_pk_fma_f32 v[26:27], v[30:31], v[20:21], v[26:27] op_sel_hi:[1,0,1]
	v_pk_fma_f32 v[28:29], v[18:19], v[28:29], 0 op_sel_hi:[0,1,0]
	s_waitcnt lgkmcnt(6)
	v_pk_fma_f32 v[26:27], v[42:43], v[16:17], v[26:27] op_sel_hi:[1,0,1]
	v_fma_f32 v19, v17, v236, -v26
	s_waitcnt lgkmcnt(0)
; #define WY_RDBLK(m_) do { _Pragma("unroll") for (int t_ = 0; t_ <= (m_); ++t_) LB[(m_) & 1][t_] = *(const LAS f32x4*)(lq + (m_) * WY_BS + 4 * t_); } while (0)
; __device__ __forceinline__ int wy_producer_task(const Ctx& c, int l, int tk, WyPre& P, unsigned* head) {
;     ...
;         for (int m = 0; m < 16; ++m) {
;             if (m + 1 < 16) WY_RDBLK(m + 1);
;             __builtin_amdgcn_sched_barrier(0);
;             f32x4 pre = (f32x4){0.f, 0.f, 0.f, 0.f};
; #pragma unroll
;             for (int t = 0; t < m; ++t) pre = LB[m & 1][t] * own[t] + pre;
; #pragma unroll
;             for (int rr = 0; rr < 4; ++rr) {
;                 float acc = ((q4 == rr) ? own[m] : 0.f) - pre[rr];
;                 if (rr > 0) acc = fmaf(-LB[m & 1][m][rr], own[m], acc);
;                 const float x = quad_sum(acc);
;                 own[m] = (q4 == rr) ? x : own[m]; }
;             __builtin_amdgcn_sched_barrier(0);
;         }
	v_fma_f32 v22, v17, v237, -v27
	v_add_f32_dpp v19, v19, v19 quad_perm:[1,0,3,2] row_mask:0xf bank_mask:0xf bound_ctrl:1
	v_pk_fma_f32 v[28:29], v[32:33], v[20:21], v[28:29] op_sel_hi:[1,0,1]
	s_nop 0
	v_add_f32_dpp v19, v19, v19 quad_perm:[2,3,0,1] row_mask:0xf bank_mask:0xf bound_ctrl:1
	v_cndmask_b32_e64 v19, v17, v19, s[6:7]
	v_fma_f32 v22, -v47, v19, v22
	v_pk_fma_f32 v[28:29], v[44:45], v[16:17], v[28:29] op_sel_hi:[1,0,1]
	s_nop 0
	v_add_f32_dpp v22, v22, v22 quad_perm:[1,0,3,2] row_mask:0xf bank_mask:0xf bound_ctrl:1
	s_nop 1
	v_add_f32_dpp v22, v22, v22 quad_perm:[2,3,0,1] row_mask:0xf bank_mask:0xf bound_ctrl:1
	v_cndmask_b32_e32 v19, v19, v22, vcc
	v_fma_f32 v22, v17, v238, -v28
	v_fma_f32 v22, -v48, v19, v22
	v_fma_f32 v17, v17, v239, -v29
	s_nop 0
	v_add_f32_dpp v22, v22, v22 quad_perm:[1,0,3,2] row_mask:0xf bank_mask:0xf bound_ctrl:1
	s_nop 1
	v_add_f32_dpp v22, v22, v22 quad_perm:[2,3,0,1] row_mask:0xf bank_mask:0xf bound_ctrl:1
	v_cndmask_b32_e64 v19, v19, v22, s[2:3]
	v_fma_f32 v17, -v49, v19, v17
	s_nop 1
	v_add_f32_dpp v17, v17, v17 quad_perm:[1,0,3,2] row_mask:0xf bank_mask:0xf bound_ctrl:1
	s_nop 1
	v_add_f32_dpp v17, v17, v17 quad_perm:[2,3,0,1] row_mask:0xf bank_mask:0xf bound_ctrl:1
	v_cndmask_b32_e64 v22, v19, v17, s[4:5]
	ds_read_b128 v[26:29], v21 offset:39744
	ds_read_b128 v[30:33], v21 offset:39760
	ds_read_b128 v[42:45], v21 offset:39776
	ds_read_b128 v[46:49], v21 offset:39792
	ds_read_b128 v[58:61], v21 offset:39808
	ds_read_b128 v[62:65], v21 offset:39824
	v_pk_fma_f32 v[34:35], v[18:19], v[34:35], 0 op_sel_hi:[0,1,0]
	v_pk_fma_f32 v[36:37], v[18:19], v[36:37], 0 op_sel_hi:[0,1,0]
	v_pk_fma_f32 v[34:35], v[38:39], v[20:21], v[34:35] op_sel_hi:[1,0,1]
	v_pk_fma_f32 v[36:37], v[40:41], v[20:21], v[36:37] op_sel_hi:[1,0,1]
	v_pk_fma_f32 v[34:35], v[50:51], v[16:17], v[34:35] op_sel_hi:[1,0,1]
	v_pk_fma_f32 v[36:37], v[52:53], v[16:17], v[36:37] op_sel_hi:[1,0,1]
	v_pk_fma_f32 v[34:35], v[54:55], v[22:23], v[34:35] op_sel_hi:[1,0,1]
	v_fma_f32 v17, v14, v236, -v34
	v_fma_f32 v19, v14, v237, -v35
	s_nop 0
	v_add_f32_dpp v17, v17, v17 quad_perm:[1,0,3,2] row_mask:0xf bank_mask:0xf bound_ctrl:1
	v_pk_fma_f32 v[36:37], v[56:57], v[22:23], v[36:37] op_sel_hi:[1,0,1]
	s_nop 0
	v_add_f32_dpp v17, v17, v17 quad_perm:[2,3,0,1] row_mask:0xf bank_mask:0xf bound_ctrl:1
	v_cndmask_b32_e64 v17, v14, v17, s[6:7]
	v_fma_f32 v19, -v23, v17, v19
	s_nop 1
	v_add_f32_dpp v19, v19, v19 quad_perm:[1,0,3,2] row_mask:0xf bank_mask:0xf bound_ctrl:1
	s_nop 1
	v_add_f32_dpp v19, v19, v19 quad_perm:[2,3,0,1] row_mask:0xf bank_mask:0xf bound_ctrl:1
	v_cndmask_b32_e32 v17, v17, v19, vcc
	v_fma_f32 v19, v14, v238, -v36
	v_fma_f32 v19, -v24, v17, v19
	v_fma_f32 v14, v14, v239, -v37
	s_nop 0
	v_add_f32_dpp v19, v19, v19 quad_perm:[1,0,3,2] row_mask:0xf bank_mask:0xf bound_ctrl:1
	s_nop 1
	v_add_f32_dpp v19, v19, v19 quad_perm:[2,3,0,1] row_mask:0xf bank_mask:0xf bound_ctrl:1
	v_cndmask_b32_e64 v17, v17, v19, s[2:3]
	v_fma_f32 v14, -v25, v17, v14
	s_nop 1
	v_add_f32_dpp v14, v14, v14 quad_perm:[1,0,3,2] row_mask:0xf bank_mask:0xf bound_ctrl:1
	s_nop 1
	v_add_f32_dpp v14, v14, v14 quad_perm:[2,3,0,1] row_mask:0xf bank_mask:0xf bound_ctrl:1
	v_cndmask_b32_e64 v14, v17, v14, s[4:5]
	ds_read_b128 v[34:37], v21 offset:40832
	ds_read_b128 v[38:41], v21 offset:40848
	ds_read_b128 v[50:53], v21 offset:40864
	ds_read_b128 v[54:57], v21 offset:40880
	ds_read_b128 v[66:69], v21 offset:40896
	ds_read_b128 v[70:73], v21 offset:40912
	ds_read_b128 v[74:77], v21 offset:40928
	s_waitcnt lgkmcnt(12)
	v_pk_fma_f32 v[26:27], v[18:19], v[26:27], 0 op_sel_hi:[0,1,0]
	s_waitcnt lgkmcnt(11)
	v_pk_fma_f32 v[26:27], v[20:21], v[30:31], v[26:27] op_sel_hi:[0,1,1]
	v_pk_fma_f32 v[24:25], v[18:19], v[28:29], 0 op_sel_hi:[0,1,0]
	s_waitcnt lgkmcnt(10)
	v_pk_fma_f32 v[26:27], v[42:43], v[16:17], v[26:27] op_sel_hi:[1,0,1]
	v_pk_fma_f32 v[24:25], v[20:21], v[32:33], v[24:25] op_sel_hi:[0,1,1]
	s_waitcnt lgkmcnt(9)
	v_pk_fma_f32 v[26:27], v[46:47], v[22:23], v[26:27] op_sel_hi:[1,0,1]
	v_pk_fma_f32 v[24:25], v[44:45], v[16:17], v[24:25] op_sel_hi:[1,0,1]
	s_waitcnt lgkmcnt(8)
	v_pk_fma_f32 v[26:27], v[58:59], v[14:15], v[26:27] op_sel_hi:[1,0,1]
	v_fma_f32 v17, v15, v236, -v26
	v_fma_f32 v19, v15, v237, -v27
	s_nop 0
	v_add_f32_dpp v17, v17, v17 quad_perm:[1,0,3,2] row_mask:0xf bank_mask:0xf bound_ctrl:1
	v_pk_fma_f32 v[24:25], v[48:49], v[22:23], v[24:25] op_sel_hi:[1,0,1]
	s_nop 0
	v_add_f32_dpp v17, v17, v17 quad_perm:[2,3,0,1] row_mask:0xf bank_mask:0xf bound_ctrl:1
	v_cndmask_b32_e64 v17, v15, v17, s[6:7]
	s_waitcnt lgkmcnt(7)
	v_fma_f32 v19, -v63, v17, v19
	v_pk_fma_f32 v[24:25], v[60:61], v[14:15], v[24:25] op_sel_hi:[1,0,1]
	s_nop 0
	v_add_f32_dpp v19, v19, v19 quad_perm:[1,0,3,2] row_mask:0xf bank_mask:0xf bound_ctrl:1
	s_nop 1
	v_add_f32_dpp v19, v19, v19 quad_perm:[2,3,0,1] row_mask:0xf bank_mask:0xf bound_ctrl:1
	v_cndmask_b32_e32 v17, v17, v19, vcc
	v_fma_f32 v19, v15, v238, -v24
	v_fma_f32 v19, -v64, v17, v19
	v_fma_f32 v15, v15, v239, -v25
	s_nop 0
	v_add_f32_dpp v19, v19, v19 quad_perm:[1,0,3,2] row_mask:0xf bank_mask:0xf bound_ctrl:1
	s_nop 1
	v_add_f32_dpp v19, v19, v19 quad_perm:[2,3,0,1] row_mask:0xf bank_mask:0xf bound_ctrl:1
	v_cndmask_b32_e64 v17, v17, v19, s[2:3]
	v_fma_f32 v15, -v65, v17, v15
	s_nop 1
	v_add_f32_dpp v15, v15, v15 quad_perm:[1,0,3,2] row_mask:0xf bank_mask:0xf bound_ctrl:1
	s_nop 1
	v_add_f32_dpp v15, v15, v15 quad_perm:[2,3,0,1] row_mask:0xf bank_mask:0xf bound_ctrl:1
	v_cndmask_b32_e64 v24, v17, v15, s[4:5]
	ds_read_b128 v[26:29], v21 offset:41920
	ds_read_b128 v[30:33], v21 offset:41936
	ds_read_b128 v[42:45], v21 offset:41952
	ds_read_b128 v[46:49], v21 offset:41968
	ds_read_b128 v[58:61], v21 offset:41984
	ds_read_b128 v[62:65], v21 offset:42000
	ds_read_b128 v[78:81], v21 offset:42016
	ds_read_b128 v[126:129], v21 offset:42032
	s_waitcnt lgkmcnt(14)
; #define WY_RDBLK(m_) do { _Pragma("unroll") for (int t_ = 0; t_ <= (m_); ++t_) LB[(m_) & 1][t_] = *(const LAS f32x4*)(lq + (m_) * WY_BS + 4 * t_); } while (0)
; __device__ __forceinline__ int wy_producer_task(const Ctx& c, int l, int tk, WyPre& P, unsigned* head) {
;     ...
;         for (int m = 0; m < 16; ++m) {
;             if (m + 1 < 16) WY_RDBLK(m + 1);
;             __builtin_amdgcn_sched_barrier(0);
;             f32x4 pre = (f32x4){0.f, 0.f, 0.f, 0.f};
; #pragma unroll
;             for (int t = 0; t < m; ++t) pre = LB[m & 1][t] * own[t] + pre;
; #pragma unroll
;             for (int rr = 0; rr < 4; ++rr) {
;                 float acc = ((q4 == rr) ? own[m] : 0.f) - pre[rr];
;                 if (rr > 0) acc = fmaf(-LB[m & 1][m][rr], own[m], acc);
;                 const float x = quad_sum(acc);
;                 own[m] = (q4 == rr) ? x : own[m]; }
;             __builtin_amdgcn_sched_barrier(0);
;         }
	v_pk_fma_f32 v[34:35], v[18:19], v[34:35], 0 op_sel_hi:[0,1,0]
	v_pk_fma_f32 v[36:37], v[18:19], v[36:37], 0 op_sel_hi:[0,1,0]
	s_waitcnt lgkmcnt(13)
	v_pk_fma_f32 v[34:35], v[20:21], v[38:39], v[34:35] op_sel_hi:[0,1,1]
	v_pk_fma_f32 v[36:37], v[20:21], v[40:41], v[36:37] op_sel_hi:[0,1,1]
	s_waitcnt lgkmcnt(12)
	v_pk_fma_f32 v[34:35], v[16:17], v[50:51], v[34:35] op_sel_hi:[0,1,1]
	v_pk_fma_f32 v[36:37], v[16:17], v[52:53], v[36:37] op_sel_hi:[0,1,1]
	s_waitcnt lgkmcnt(11)
	v_pk_fma_f32 v[34:35], v[54:55], v[22:23], v[34:35] op_sel_hi:[1,0,1]
	v_pk_fma_f32 v[36:37], v[56:57], v[22:23], v[36:37] op_sel_hi:[1,0,1]
	s_waitcnt lgkmcnt(10)
	v_pk_fma_f32 v[34:35], v[66:67], v[14:15], v[34:35] op_sel_hi:[1,0,1]
	v_pk_fma_f32 v[36:37], v[68:69], v[14:15], v[36:37] op_sel_hi:[1,0,1]
	s_waitcnt lgkmcnt(9)
	v_pk_fma_f32 v[34:35], v[70:71], v[24:25], v[34:35] op_sel_hi:[1,0,1]
	v_fma_f32 v15, v12, v236, -v34
	v_fma_f32 v17, v12, v237, -v35
	s_nop 0
	v_add_f32_dpp v15, v15, v15 quad_perm:[1,0,3,2] row_mask:0xf bank_mask:0xf bound_ctrl:1
	v_pk_fma_f32 v[36:37], v[72:73], v[24:25], v[36:37] op_sel_hi:[1,0,1]
	s_nop 0
	v_add_f32_dpp v15, v15, v15 quad_perm:[2,3,0,1] row_mask:0xf bank_mask:0xf bound_ctrl:1
	v_cndmask_b32_e64 v15, v12, v15, s[6:7]
	s_waitcnt lgkmcnt(8)
	v_fma_f32 v17, -v75, v15, v17
	s_nop 1
	v_add_f32_dpp v17, v17, v17 quad_perm:[1,0,3,2] row_mask:0xf bank_mask:0xf bound_ctrl:1
	s_nop 1
	v_add_f32_dpp v17, v17, v17 quad_perm:[2,3,0,1] row_mask:0xf bank_mask:0xf bound_ctrl:1
	v_cndmask_b32_e32 v15, v15, v17, vcc
	v_fma_f32 v17, v12, v238, -v36
	v_fma_f32 v17, -v76, v15, v17
	v_fma_f32 v12, v12, v239, -v37
	s_nop 0
	v_add_f32_dpp v17, v17, v17 quad_perm:[1,0,3,2] row_mask:0xf bank_mask:0xf bound_ctrl:1
	s_nop 1
	v_add_f32_dpp v17, v17, v17 quad_perm:[2,3,0,1] row_mask:0xf bank_mask:0xf bound_ctrl:1
	v_cndmask_b32_e64 v15, v15, v17, s[2:3]
	v_fma_f32 v12, -v77, v15, v12
	s_nop 1
	v_add_f32_dpp v12, v12, v12 quad_perm:[1,0,3,2] row_mask:0xf bank_mask:0xf bound_ctrl:1
	s_nop 1
	v_add_f32_dpp v12, v12, v12 quad_perm:[2,3,0,1] row_mask:0xf bank_mask:0xf bound_ctrl:1
	v_cndmask_b32_e64 v12, v15, v12, s[4:5]
	ds_read_b128 v[34:37], v21 offset:43008
	ds_read_b128 v[38:41], v21 offset:43024
	ds_read_b128 v[50:53], v21 offset:43040
	ds_read_b128 v[54:57], v21 offset:43056
	ds_read_b128 v[66:69], v21 offset:43072
	ds_read_b128 v[70:73], v21 offset:43088
	ds_read_b128 v[74:77], v21 offset:43104
	ds_read_b128 v[130:133], v21 offset:43120
	ds_read_b128 v[134:137], v21 offset:43136
	s_waitcnt lgkmcnt(14)
	v_pk_fma_f32 v[26:27], v[18:19], v[26:27], 0 op_sel_hi:[0,1,0]
	v_pk_fma_f32 v[26:27], v[20:21], v[30:31], v[26:27] op_sel_hi:[0,1,1]
	v_pk_fma_f32 v[28:29], v[18:19], v[28:29], 0 op_sel_hi:[0,1,0]
	v_pk_fma_f32 v[26:27], v[16:17], v[42:43], v[26:27] op_sel_hi:[0,1,1]
	v_pk_fma_f32 v[28:29], v[20:21], v[32:33], v[28:29] op_sel_hi:[0,1,1]
	s_waitcnt lgkmcnt(13)
	v_pk_fma_f32 v[26:27], v[22:23], v[46:47], v[26:27] op_sel_hi:[0,1,1]
	v_pk_fma_f32 v[28:29], v[16:17], v[44:45], v[28:29] op_sel_hi:[0,1,1]
	s_waitcnt lgkmcnt(12)
	v_pk_fma_f32 v[26:27], v[58:59], v[14:15], v[26:27] op_sel_hi:[1,0,1]
	v_pk_fma_f32 v[28:29], v[22:23], v[48:49], v[28:29] op_sel_hi:[0,1,1]
	s_waitcnt lgkmcnt(11)
	v_pk_fma_f32 v[26:27], v[62:63], v[24:25], v[26:27] op_sel_hi:[1,0,1]
	v_pk_fma_f32 v[28:29], v[60:61], v[14:15], v[28:29] op_sel_hi:[1,0,1]
	s_waitcnt lgkmcnt(10)
	v_pk_fma_f32 v[26:27], v[78:79], v[12:13], v[26:27] op_sel_hi:[1,0,1]
	v_fma_f32 v15, v13, v236, -v26
	v_fma_f32 v17, v13, v237, -v27
	s_nop 0
	v_add_f32_dpp v15, v15, v15 quad_perm:[1,0,3,2] row_mask:0xf bank_mask:0xf bound_ctrl:1
	v_pk_fma_f32 v[28:29], v[64:65], v[24:25], v[28:29] op_sel_hi:[1,0,1]
	s_nop 0
	v_add_f32_dpp v15, v15, v15 quad_perm:[2,3,0,1] row_mask:0xf bank_mask:0xf bound_ctrl:1
	v_cndmask_b32_e64 v15, v13, v15, s[6:7]
	s_waitcnt lgkmcnt(9)
	v_fma_f32 v17, -v127, v15, v17
	v_pk_fma_f32 v[28:29], v[80:81], v[12:13], v[28:29] op_sel_hi:[1,0,1]
	s_nop 0
	v_add_f32_dpp v17, v17, v17 quad_perm:[1,0,3,2] row_mask:0xf bank_mask:0xf bound_ctrl:1
	s_nop 1
	v_add_f32_dpp v17, v17, v17 quad_perm:[2,3,0,1] row_mask:0xf bank_mask:0xf bound_ctrl:1
	v_cndmask_b32_e32 v15, v15, v17, vcc
	v_fma_f32 v17, v13, v238, -v28
	v_fma_f32 v17, -v128, v15, v17
	v_fma_f32 v13, v13, v239, -v29
	s_nop 0
	v_add_f32_dpp v17, v17, v17 quad_perm:[1,0,3,2] row_mask:0xf bank_mask:0xf bound_ctrl:1
	s_nop 1
	v_add_f32_dpp v17, v17, v17 quad_perm:[2,3,0,1] row_mask:0xf bank_mask:0xf bound_ctrl:1
	v_cndmask_b32_e64 v15, v15, v17, s[2:3]
	v_fma_f32 v13, -v129, v15, v13
	s_nop 1
	v_add_f32_dpp v13, v13, v13 quad_perm:[1,0,3,2] row_mask:0xf bank_mask:0xf bound_ctrl:1
	s_nop 1
	v_add_f32_dpp v13, v13, v13 quad_perm:[2,3,0,1] row_mask:0xf bank_mask:0xf bound_ctrl:1
	v_cndmask_b32_e64 v26, v15, v13, s[4:5]
	ds_read_b128 v[28:31], v21 offset:44096
	ds_read_b128 v[42:45], v21 offset:44112
	ds_read_b128 v[46:49], v21 offset:44128
	ds_read_b128 v[58:61], v21 offset:44144
	ds_read_b128 v[62:65], v21 offset:44160
	ds_read_b128 v[78:81], v21 offset:44176
	ds_read_b128 v[126:129], v21 offset:44192
	ds_read_b128 v[138:141], v21 offset:44208
	ds_read_b128 v[142:145], v21 offset:44224
	ds_read_b128 v[146:149], v21 offset:44240
	s_waitcnt lgkmcnt(14)
	v_pk_fma_f32 v[32:33], v[18:19], v[34:35], 0 op_sel_hi:[0,1,0]
	v_pk_fma_f32 v[34:35], v[18:19], v[36:37], 0 op_sel_hi:[0,1,0]
	v_pk_fma_f32 v[32:33], v[20:21], v[38:39], v[32:33] op_sel_hi:[0,1,1]
	v_pk_fma_f32 v[34:35], v[20:21], v[40:41], v[34:35] op_sel_hi:[0,1,1]
	v_pk_fma_f32 v[32:33], v[16:17], v[50:51], v[32:33] op_sel_hi:[0,1,1]
	v_pk_fma_f32 v[34:35], v[16:17], v[52:53], v[34:35] op_sel_hi:[0,1,1]
	v_pk_fma_f32 v[32:33], v[22:23], v[54:55], v[32:33] op_sel_hi:[0,1,1]
	v_pk_fma_f32 v[34:35], v[22:23], v[56:57], v[34:35] op_sel_hi:[0,1,1]
	v_pk_fma_f32 v[32:33], v[14:15], v[66:67], v[32:33] op_sel_hi:[0,1,1]
	v_pk_fma_f32 v[34:35], v[14:15], v[68:69], v[34:35] op_sel_hi:[0,1,1]
	s_waitcnt lgkmcnt(13)
; #define WY_RDBLK(m_) do { _Pragma("unroll") for (int t_ = 0; t_ <= (m_); ++t_) LB[(m_) & 1][t_] = *(const LAS f32x4*)(lq + (m_) * WY_BS + 4 * t_); } while (0)
; __device__ __forceinline__ int wy_producer_task(const Ctx& c, int l, int tk, WyPre& P, unsigned* head) {
;     ...
;         for (int m = 0; m < 16; ++m) {
;             if (m + 1 < 16) WY_RDBLK(m + 1);
;             __builtin_amdgcn_sched_barrier(0);
;             f32x4 pre = (f32x4){0.f, 0.f, 0.f, 0.f};
; #pragma unroll
;             for (int t = 0; t < m; ++t) pre = LB[m & 1][t] * own[t] + pre;
; #pragma unroll
;             for (int rr = 0; rr < 4; ++rr) {
;                 float acc = ((q4 == rr) ? own[m] : 0.f) - pre[rr];
;                 if (rr > 0) acc = fmaf(-LB[m & 1][m][rr], own[m], acc);
;                 const float x = quad_sum(acc);
;                 own[m] = (q4 == rr) ? x : own[m]; }
;             __builtin_amdgcn_sched_barrier(0);
;         }
	v_pk_fma_f32 v[32:33], v[70:71], v[24:25], v[32:33] op_sel_hi:[1,0,1]
	v_pk_fma_f32 v[34:35], v[72:73], v[24:25], v[34:35] op_sel_hi:[1,0,1]
	s_waitcnt lgkmcnt(12)
	v_pk_fma_f32 v[32:33], v[74:75], v[12:13], v[32:33] op_sel_hi:[1,0,1]
	v_pk_fma_f32 v[34:35], v[76:77], v[12:13], v[34:35] op_sel_hi:[1,0,1]
	s_waitcnt lgkmcnt(11)
	v_pk_fma_f32 v[32:33], v[130:131], v[26:27], v[32:33] op_sel_hi:[1,0,1]
	v_fma_f32 v13, v10, v236, -v32
	v_fma_f32 v15, v10, v237, -v33
	s_nop 0
	v_add_f32_dpp v13, v13, v13 quad_perm:[1,0,3,2] row_mask:0xf bank_mask:0xf bound_ctrl:1
	v_pk_fma_f32 v[34:35], v[132:133], v[26:27], v[34:35] op_sel_hi:[1,0,1]
	s_nop 0
	v_add_f32_dpp v13, v13, v13 quad_perm:[2,3,0,1] row_mask:0xf bank_mask:0xf bound_ctrl:1
	v_cndmask_b32_e64 v13, v10, v13, s[6:7]
	s_waitcnt lgkmcnt(10)
	v_fma_f32 v15, -v135, v13, v15
	s_nop 1
	v_add_f32_dpp v15, v15, v15 quad_perm:[1,0,3,2] row_mask:0xf bank_mask:0xf bound_ctrl:1
	s_nop 1
	v_add_f32_dpp v15, v15, v15 quad_perm:[2,3,0,1] row_mask:0xf bank_mask:0xf bound_ctrl:1
	v_cndmask_b32_e32 v13, v13, v15, vcc
	v_fma_f32 v15, v10, v238, -v34
	v_fma_f32 v15, -v136, v13, v15
	v_fma_f32 v10, v10, v239, -v35
	s_nop 0
	v_add_f32_dpp v15, v15, v15 quad_perm:[1,0,3,2] row_mask:0xf bank_mask:0xf bound_ctrl:1
	s_nop 1
	v_add_f32_dpp v15, v15, v15 quad_perm:[2,3,0,1] row_mask:0xf bank_mask:0xf bound_ctrl:1
	v_cndmask_b32_e64 v13, v13, v15, s[2:3]
	v_fma_f32 v10, -v137, v13, v10
	s_nop 1
	v_add_f32_dpp v10, v10, v10 quad_perm:[1,0,3,2] row_mask:0xf bank_mask:0xf bound_ctrl:1
	s_nop 1
	v_add_f32_dpp v10, v10, v10 quad_perm:[2,3,0,1] row_mask:0xf bank_mask:0xf bound_ctrl:1
	v_cndmask_b32_e64 v10, v13, v10, s[4:5]
	ds_read_b128 v[32:35], v21 offset:45184
	ds_read_b128 v[36:39], v21 offset:45200
	ds_read_b128 v[50:53], v21 offset:45216
	ds_read_b128 v[54:57], v21 offset:45232
	ds_read_b128 v[66:69], v21 offset:45248
	ds_read_b128 v[70:73], v21 offset:45264
	ds_read_b128 v[74:77], v21 offset:45280
	ds_read_b128 v[130:133], v21 offset:45296
	ds_read_b128 v[134:137], v21 offset:45312
	ds_read_b128 v[150:153], v21 offset:45328
	ds_read_b128 v[154:157], v21 offset:45344
	s_waitcnt lgkmcnt(14)
	v_pk_fma_f32 v[28:29], v[18:19], v[28:29], 0 op_sel_hi:[0,1,0]
	v_pk_fma_f32 v[28:29], v[20:21], v[42:43], v[28:29] op_sel_hi:[0,1,1]
	v_pk_fma_f32 v[30:31], v[18:19], v[30:31], 0 op_sel_hi:[0,1,0]
	v_pk_fma_f32 v[28:29], v[16:17], v[46:47], v[28:29] op_sel_hi:[0,1,1]
	v_pk_fma_f32 v[30:31], v[20:21], v[44:45], v[30:31] op_sel_hi:[0,1,1]
	v_pk_fma_f32 v[28:29], v[22:23], v[58:59], v[28:29] op_sel_hi:[0,1,1]
	v_pk_fma_f32 v[30:31], v[16:17], v[48:49], v[30:31] op_sel_hi:[0,1,1]
	v_pk_fma_f32 v[28:29], v[14:15], v[62:63], v[28:29] op_sel_hi:[0,1,1]
	v_pk_fma_f32 v[30:31], v[22:23], v[60:61], v[30:31] op_sel_hi:[0,1,1]
	v_pk_fma_f32 v[28:29], v[24:25], v[78:79], v[28:29] op_sel_hi:[0,1,1]
	v_pk_fma_f32 v[30:31], v[14:15], v[64:65], v[30:31] op_sel_hi:[0,1,1]
	v_pk_fma_f32 v[28:29], v[126:127], v[12:13], v[28:29] op_sel_hi:[1,0,1]
	v_pk_fma_f32 v[30:31], v[24:25], v[80:81], v[30:31] op_sel_hi:[0,1,1]
	s_waitcnt lgkmcnt(13)
	v_pk_fma_f32 v[28:29], v[138:139], v[26:27], v[28:29] op_sel_hi:[1,0,1]
	v_pk_fma_f32 v[30:31], v[128:129], v[12:13], v[30:31] op_sel_hi:[1,0,1]
	s_waitcnt lgkmcnt(12)
	v_pk_fma_f32 v[28:29], v[142:143], v[10:11], v[28:29] op_sel_hi:[1,0,1]
	v_fma_f32 v13, v11, v236, -v28
	v_fma_f32 v15, v11, v237, -v29
	s_nop 0
	v_add_f32_dpp v13, v13, v13 quad_perm:[1,0,3,2] row_mask:0xf bank_mask:0xf bound_ctrl:1
	v_pk_fma_f32 v[30:31], v[140:141], v[26:27], v[30:31] op_sel_hi:[1,0,1]
	s_nop 0
	v_add_f32_dpp v13, v13, v13 quad_perm:[2,3,0,1] row_mask:0xf bank_mask:0xf bound_ctrl:1
	v_cndmask_b32_e64 v13, v11, v13, s[6:7]
	s_waitcnt lgkmcnt(11)
	v_fma_f32 v15, -v147, v13, v15
	v_pk_fma_f32 v[30:31], v[144:145], v[10:11], v[30:31] op_sel_hi:[1,0,1]
	s_nop 0
	v_add_f32_dpp v15, v15, v15 quad_perm:[1,0,3,2] row_mask:0xf bank_mask:0xf bound_ctrl:1
	s_nop 1
	v_add_f32_dpp v15, v15, v15 quad_perm:[2,3,0,1] row_mask:0xf bank_mask:0xf bound_ctrl:1
	v_cndmask_b32_e32 v13, v13, v15, vcc
	v_fma_f32 v15, v11, v238, -v30
	v_fma_f32 v15, -v148, v13, v15
	v_fma_f32 v11, v11, v239, -v31
	s_nop 0
	v_add_f32_dpp v15, v15, v15 quad_perm:[1,0,3,2] row_mask:0xf bank_mask:0xf bound_ctrl:1
	s_nop 1
	v_add_f32_dpp v15, v15, v15 quad_perm:[2,3,0,1] row_mask:0xf bank_mask:0xf bound_ctrl:1
	v_cndmask_b32_e64 v13, v13, v15, s[2:3]
	v_fma_f32 v11, -v149, v13, v11
	s_nop 1
	v_add_f32_dpp v11, v11, v11 quad_perm:[1,0,3,2] row_mask:0xf bank_mask:0xf bound_ctrl:1
	s_nop 1
	v_add_f32_dpp v11, v11, v11 quad_perm:[2,3,0,1] row_mask:0xf bank_mask:0xf bound_ctrl:1
	v_cndmask_b32_e64 v28, v13, v11, s[4:5]
	ds_read_b128 v[40:43], v21 offset:46272
	ds_read_b128 v[44:47], v21 offset:46288
	ds_read_b128 v[58:61], v21 offset:46304
	ds_read_b128 v[62:65], v21 offset:46320
	ds_read_b128 v[78:81], v21 offset:46336
	ds_read_b128 v[126:129], v21 offset:46352
	ds_read_b128 v[138:141], v21 offset:46368
	ds_read_b128 v[142:145], v21 offset:46384
	ds_read_b128 v[146:149], v21 offset:46400
	ds_read_b128 v[158:161], v21 offset:46416
	ds_read_b128 v[162:165], v21 offset:46432
	ds_read_b128 v[166:169], v21 offset:46448
	s_waitcnt lgkmcnt(14)
; #define WY_RDBLK(m_) do { _Pragma("unroll") for (int t_ = 0; t_ <= (m_); ++t_) LB[(m_) & 1][t_] = *(const LAS f32x4*)(lq + (m_) * WY_BS + 4 * t_); } while (0)
; __device__ __forceinline__ int wy_producer_task(const Ctx& c, int l, int tk, WyPre& P, unsigned* head) {
;     ...
;         for (int m = 0; m < 16; ++m) {
;             if (m + 1 < 16) WY_RDBLK(m + 1);
;             __builtin_amdgcn_sched_barrier(0);
;             f32x4 pre = (f32x4){0.f, 0.f, 0.f, 0.f};
; #pragma unroll
;             for (int t = 0; t < m; ++t) pre = LB[m & 1][t] * own[t] + pre;
; #pragma unroll
;             for (int rr = 0; rr < 4; ++rr) {
;                 float acc = ((q4 == rr) ? own[m] : 0.f) - pre[rr];
;                 if (rr > 0) acc = fmaf(-LB[m & 1][m][rr], own[m], acc);
;                 const float x = quad_sum(acc);
;                 own[m] = (q4 == rr) ? x : own[m]; }
;             __builtin_amdgcn_sched_barrier(0);
;         }
	v_pk_fma_f32 v[30:31], v[18:19], v[32:33], 0 op_sel_hi:[0,1,0]
	v_pk_fma_f32 v[32:33], v[18:19], v[34:35], 0 op_sel_hi:[0,1,0]
	v_pk_fma_f32 v[30:31], v[20:21], v[36:37], v[30:31] op_sel_hi:[0,1,1]
	v_pk_fma_f32 v[32:33], v[20:21], v[38:39], v[32:33] op_sel_hi:[0,1,1]
	v_pk_fma_f32 v[30:31], v[16:17], v[50:51], v[30:31] op_sel_hi:[0,1,1]
	v_pk_fma_f32 v[32:33], v[16:17], v[52:53], v[32:33] op_sel_hi:[0,1,1]
	v_pk_fma_f32 v[30:31], v[22:23], v[54:55], v[30:31] op_sel_hi:[0,1,1]
	v_pk_fma_f32 v[32:33], v[22:23], v[56:57], v[32:33] op_sel_hi:[0,1,1]
	v_pk_fma_f32 v[30:31], v[14:15], v[66:67], v[30:31] op_sel_hi:[0,1,1]
	v_pk_fma_f32 v[32:33], v[14:15], v[68:69], v[32:33] op_sel_hi:[0,1,1]
	v_pk_fma_f32 v[30:31], v[24:25], v[70:71], v[30:31] op_sel_hi:[0,1,1]
	v_pk_fma_f32 v[32:33], v[24:25], v[72:73], v[32:33] op_sel_hi:[0,1,1]
	v_pk_fma_f32 v[30:31], v[12:13], v[74:75], v[30:31] op_sel_hi:[0,1,1]
	v_pk_fma_f32 v[32:33], v[12:13], v[76:77], v[32:33] op_sel_hi:[0,1,1]
	v_pk_fma_f32 v[30:31], v[130:131], v[26:27], v[30:31] op_sel_hi:[1,0,1]
	v_pk_fma_f32 v[32:33], v[132:133], v[26:27], v[32:33] op_sel_hi:[1,0,1]
	v_pk_fma_f32 v[30:31], v[134:135], v[10:11], v[30:31] op_sel_hi:[1,0,1]
	v_pk_fma_f32 v[32:33], v[136:137], v[10:11], v[32:33] op_sel_hi:[1,0,1]
	s_waitcnt lgkmcnt(13)
	v_pk_fma_f32 v[30:31], v[150:151], v[28:29], v[30:31] op_sel_hi:[1,0,1]
	v_fma_f32 v11, v8, v236, -v30
	v_fma_f32 v13, v8, v237, -v31
	s_nop 0
	v_add_f32_dpp v11, v11, v11 quad_perm:[1,0,3,2] row_mask:0xf bank_mask:0xf bound_ctrl:1
	v_pk_fma_f32 v[32:33], v[152:153], v[28:29], v[32:33] op_sel_hi:[1,0,1]
	s_nop 0
	v_add_f32_dpp v11, v11, v11 quad_perm:[2,3,0,1] row_mask:0xf bank_mask:0xf bound_ctrl:1
	v_cndmask_b32_e64 v11, v8, v11, s[6:7]
	s_waitcnt lgkmcnt(12)
	v_fma_f32 v13, -v155, v11, v13
	s_nop 1
	v_add_f32_dpp v13, v13, v13 quad_perm:[1,0,3,2] row_mask:0xf bank_mask:0xf bound_ctrl:1
	s_nop 1
	v_add_f32_dpp v13, v13, v13 quad_perm:[2,3,0,1] row_mask:0xf bank_mask:0xf bound_ctrl:1
	v_cndmask_b32_e32 v11, v11, v13, vcc
	v_fma_f32 v13, v8, v238, -v32
	v_fma_f32 v13, -v156, v11, v13
	v_fma_f32 v8, v8, v239, -v33
	s_nop 0
	v_add_f32_dpp v13, v13, v13 quad_perm:[1,0,3,2] row_mask:0xf bank_mask:0xf bound_ctrl:1
	s_nop 1
	v_add_f32_dpp v13, v13, v13 quad_perm:[2,3,0,1] row_mask:0xf bank_mask:0xf bound_ctrl:1
	v_cndmask_b32_e64 v11, v11, v13, s[2:3]
	v_fma_f32 v8, -v157, v11, v8
	s_nop 1
	v_add_f32_dpp v8, v8, v8 quad_perm:[1,0,3,2] row_mask:0xf bank_mask:0xf bound_ctrl:1
	s_nop 1
	v_add_f32_dpp v8, v8, v8 quad_perm:[2,3,0,1] row_mask:0xf bank_mask:0xf bound_ctrl:1
	v_cndmask_b32_e64 v8, v11, v8, s[4:5]
	ds_read_b128 v[32:35], v21 offset:47360
	ds_read_b128 v[36:39], v21 offset:47376
	ds_read_b128 v[48:51], v21 offset:47392
	ds_read_b128 v[52:55], v21 offset:47408
	ds_read_b128 v[66:69], v21 offset:47424
	ds_read_b128 v[70:73], v21 offset:47440
	ds_read_b128 v[74:77], v21 offset:47456
	ds_read_b128 v[130:133], v21 offset:47472
	ds_read_b128 v[134:137], v21 offset:47488
	ds_read_b128 v[150:153], v21 offset:47504
	ds_read_b128 v[154:157], v21 offset:47520
	ds_read_b128 v[170:173], v21 offset:47536
	ds_read_b128 v[174:177], v21 offset:47552
	s_waitcnt lgkmcnt(14)
	v_pk_fma_f32 v[40:41], v[18:19], v[40:41], 0 op_sel_hi:[0,1,0]
	v_pk_fma_f32 v[40:41], v[20:21], v[44:45], v[40:41] op_sel_hi:[0,1,1]
	v_pk_fma_f32 v[30:31], v[18:19], v[42:43], 0 op_sel_hi:[0,1,0]
	v_pk_fma_f32 v[40:41], v[16:17], v[58:59], v[40:41] op_sel_hi:[0,1,1]
	v_pk_fma_f32 v[30:31], v[20:21], v[46:47], v[30:31] op_sel_hi:[0,1,1]
	v_pk_fma_f32 v[40:41], v[22:23], v[62:63], v[40:41] op_sel_hi:[0,1,1]
	v_pk_fma_f32 v[30:31], v[16:17], v[60:61], v[30:31] op_sel_hi:[0,1,1]
	v_pk_fma_f32 v[40:41], v[14:15], v[78:79], v[40:41] op_sel_hi:[0,1,1]
	v_pk_fma_f32 v[30:31], v[22:23], v[64:65], v[30:31] op_sel_hi:[0,1,1]
	v_pk_fma_f32 v[40:41], v[24:25], v[126:127], v[40:41] op_sel_hi:[0,1,1]
	v_pk_fma_f32 v[30:31], v[14:15], v[80:81], v[30:31] op_sel_hi:[0,1,1]
	v_pk_fma_f32 v[40:41], v[12:13], v[138:139], v[40:41] op_sel_hi:[0,1,1]
	v_pk_fma_f32 v[30:31], v[24:25], v[128:129], v[30:31] op_sel_hi:[0,1,1]
	v_pk_fma_f32 v[40:41], v[26:27], v[142:143], v[40:41] op_sel_hi:[0,1,1]
	v_pk_fma_f32 v[30:31], v[12:13], v[140:141], v[30:31] op_sel_hi:[0,1,1]
	v_pk_fma_f32 v[40:41], v[146:147], v[10:11], v[40:41] op_sel_hi:[1,0,1]
	v_pk_fma_f32 v[30:31], v[26:27], v[144:145], v[30:31] op_sel_hi:[0,1,1]
	v_pk_fma_f32 v[40:41], v[158:159], v[28:29], v[40:41] op_sel_hi:[1,0,1]
	v_pk_fma_f32 v[30:31], v[148:149], v[10:11], v[30:31] op_sel_hi:[1,0,1]
	v_pk_fma_f32 v[40:41], v[162:163], v[8:9], v[40:41] op_sel_hi:[1,0,1]
	v_fma_f32 v11, v9, v236, -v40
	v_fma_f32 v13, v9, v237, -v41
	s_nop 0
	v_add_f32_dpp v11, v11, v11 quad_perm:[1,0,3,2] row_mask:0xf bank_mask:0xf bound_ctrl:1
	v_pk_fma_f32 v[30:31], v[160:161], v[28:29], v[30:31] op_sel_hi:[1,0,1]
	s_nop 0
	v_add_f32_dpp v11, v11, v11 quad_perm:[2,3,0,1] row_mask:0xf bank_mask:0xf bound_ctrl:1
	v_cndmask_b32_e64 v11, v9, v11, s[6:7]
	s_waitcnt lgkmcnt(13)
; #define WY_RDBLK(m_) do { _Pragma("unroll") for (int t_ = 0; t_ <= (m_); ++t_) LB[(m_) & 1][t_] = *(const LAS f32x4*)(lq + (m_) * WY_BS + 4 * t_); } while (0)
; __device__ __forceinline__ int wy_producer_task(const Ctx& c, int l, int tk, WyPre& P, unsigned* head) {
;     ...
; #pragma unroll
;         for (int m = 0; m < 16; ++m) {
;             if (m + 1 < 16) WY_RDBLK(m + 1);
;             __builtin_amdgcn_sched_barrier(0);
;             f32x4 pre = (f32x4){0.f, 0.f, 0.f, 0.f};
; #pragma unroll
;             for (int t = 0; t < m; ++t) pre = LB[m & 1][t] * own[t] + pre;
; #pragma unroll
;             for (int rr = 0; rr < 4; ++rr) {
;                 float acc = ((q4 == rr) ? own[m] : 0.f) - pre[rr];
;                 if (rr > 0) acc = fmaf(-LB[m & 1][m][rr], own[m], acc);
;                 const float x = quad_sum(acc);
;                 own[m] = (q4 == rr) ? x : own[m]; }
;             __builtin_amdgcn_sched_barrier(0);
	v_fma_f32 v13, -v167, v11, v13
	v_pk_fma_f32 v[30:31], v[164:165], v[8:9], v[30:31] op_sel_hi:[1,0,1]
	s_nop 0
	v_add_f32_dpp v13, v13, v13 quad_perm:[1,0,3,2] row_mask:0xf bank_mask:0xf bound_ctrl:1
	s_nop 1
	v_add_f32_dpp v13, v13, v13 quad_perm:[2,3,0,1] row_mask:0xf bank_mask:0xf bound_ctrl:1
	v_cndmask_b32_e32 v11, v11, v13, vcc
	v_fma_f32 v13, v9, v238, -v30
	v_fma_f32 v13, -v168, v11, v13
	v_fma_f32 v9, v9, v239, -v31
	s_nop 0
	v_add_f32_dpp v13, v13, v13 quad_perm:[1,0,3,2] row_mask:0xf bank_mask:0xf bound_ctrl:1
	s_nop 1
	v_add_f32_dpp v13, v13, v13 quad_perm:[2,3,0,1] row_mask:0xf bank_mask:0xf bound_ctrl:1
	v_cndmask_b32_e64 v11, v11, v13, s[2:3]
	v_fma_f32 v9, -v169, v11, v9
	s_nop 1
	v_add_f32_dpp v9, v9, v9 quad_perm:[1,0,3,2] row_mask:0xf bank_mask:0xf bound_ctrl:1
	s_nop 1
	v_add_f32_dpp v9, v9, v9 quad_perm:[2,3,0,1] row_mask:0xf bank_mask:0xf bound_ctrl:1
	v_cndmask_b32_e64 v30, v11, v9, s[4:5]
	ds_read_b128 v[40:43], v21 offset:48448
	ds_read_b128 v[44:47], v21 offset:48464
	ds_read_b128 v[56:59], v21 offset:48480
	ds_read_b128 v[60:63], v21 offset:48496
	ds_read_b128 v[78:81], v21 offset:48512
	ds_read_b128 v[126:129], v21 offset:48528
	ds_read_b128 v[138:141], v21 offset:48544
	ds_read_b128 v[142:145], v21 offset:48560
	ds_read_b128 v[146:149], v21 offset:48576
	ds_read_b128 v[158:161], v21 offset:48592
	ds_read_b128 v[162:165], v21 offset:48608
	ds_read_b128 v[166:169], v21 offset:48624
	ds_read_b128 v[178:181], v21 offset:48640
	ds_read_b128 v[182:185], v21 offset:48656
	s_waitcnt lgkmcnt(14)
	v_pk_fma_f32 v[32:33], v[18:19], v[32:33], 0 op_sel_hi:[0,1,0]
	v_pk_fma_f32 v[34:35], v[18:19], v[34:35], 0 op_sel_hi:[0,1,0]
	v_pk_fma_f32 v[32:33], v[20:21], v[36:37], v[32:33] op_sel_hi:[0,1,1]
	v_pk_fma_f32 v[34:35], v[20:21], v[38:39], v[34:35] op_sel_hi:[0,1,1]
	v_pk_fma_f32 v[32:33], v[16:17], v[48:49], v[32:33] op_sel_hi:[0,1,1]
	v_pk_fma_f32 v[34:35], v[16:17], v[50:51], v[34:35] op_sel_hi:[0,1,1]
	v_pk_fma_f32 v[32:33], v[22:23], v[52:53], v[32:33] op_sel_hi:[0,1,1]
	v_pk_fma_f32 v[34:35], v[22:23], v[54:55], v[34:35] op_sel_hi:[0,1,1]
	v_pk_fma_f32 v[32:33], v[14:15], v[66:67], v[32:33] op_sel_hi:[0,1,1]
	v_pk_fma_f32 v[34:35], v[14:15], v[68:69], v[34:35] op_sel_hi:[0,1,1]
	v_pk_fma_f32 v[32:33], v[24:25], v[70:71], v[32:33] op_sel_hi:[0,1,1]
	v_pk_fma_f32 v[34:35], v[24:25], v[72:73], v[34:35] op_sel_hi:[0,1,1]
	v_pk_fma_f32 v[32:33], v[12:13], v[74:75], v[32:33] op_sel_hi:[0,1,1]
	v_pk_fma_f32 v[34:35], v[12:13], v[76:77], v[34:35] op_sel_hi:[0,1,1]
	v_pk_fma_f32 v[32:33], v[26:27], v[130:131], v[32:33] op_sel_hi:[0,1,1]
	v_pk_fma_f32 v[34:35], v[26:27], v[132:133], v[34:35] op_sel_hi:[0,1,1]
	v_pk_fma_f32 v[32:33], v[10:11], v[134:135], v[32:33] op_sel_hi:[0,1,1]
	v_pk_fma_f32 v[34:35], v[10:11], v[136:137], v[34:35] op_sel_hi:[0,1,1]
	v_pk_fma_f32 v[32:33], v[150:151], v[28:29], v[32:33] op_sel_hi:[1,0,1]
	v_pk_fma_f32 v[34:35], v[152:153], v[28:29], v[34:35] op_sel_hi:[1,0,1]
	v_pk_fma_f32 v[32:33], v[154:155], v[8:9], v[32:33] op_sel_hi:[1,0,1]
	v_pk_fma_f32 v[34:35], v[156:157], v[8:9], v[34:35] op_sel_hi:[1,0,1]
	v_pk_fma_f32 v[32:33], v[170:171], v[30:31], v[32:33] op_sel_hi:[1,0,1]
	v_fma_f32 v9, v6, v236, -v32
	v_fma_f32 v11, v6, v237, -v33
	s_nop 0
	v_add_f32_dpp v9, v9, v9 quad_perm:[1,0,3,2] row_mask:0xf bank_mask:0xf bound_ctrl:1
	v_pk_fma_f32 v[34:35], v[172:173], v[30:31], v[34:35] op_sel_hi:[1,0,1]
	s_nop 0
	v_add_f32_dpp v9, v9, v9 quad_perm:[2,3,0,1] row_mask:0xf bank_mask:0xf bound_ctrl:1
	v_cndmask_b32_e64 v9, v6, v9, s[6:7]
	v_fma_f32 v11, -v175, v9, v11
	s_nop 1
	v_add_f32_dpp v11, v11, v11 quad_perm:[1,0,3,2] row_mask:0xf bank_mask:0xf bound_ctrl:1
	s_nop 1
	v_add_f32_dpp v11, v11, v11 quad_perm:[2,3,0,1] row_mask:0xf bank_mask:0xf bound_ctrl:1
	v_cndmask_b32_e32 v9, v9, v11, vcc
	v_fma_f32 v11, v6, v238, -v34
	v_fma_f32 v11, -v176, v9, v11
	v_fma_f32 v6, v6, v239, -v35
	s_nop 0
	v_add_f32_dpp v11, v11, v11 quad_perm:[1,0,3,2] row_mask:0xf bank_mask:0xf bound_ctrl:1
	s_nop 1
	v_add_f32_dpp v11, v11, v11 quad_perm:[2,3,0,1] row_mask:0xf bank_mask:0xf bound_ctrl:1
	v_cndmask_b32_e64 v9, v9, v11, s[2:3]
	v_fma_f32 v6, -v177, v9, v6
	s_nop 1
	v_add_f32_dpp v6, v6, v6 quad_perm:[1,0,3,2] row_mask:0xf bank_mask:0xf bound_ctrl:1
	s_nop 1
	v_add_f32_dpp v6, v6, v6 quad_perm:[2,3,0,1] row_mask:0xf bank_mask:0xf bound_ctrl:1
	v_cndmask_b32_e64 v6, v9, v6, s[4:5]
	ds_read_b128 v[34:37], v21 offset:49536
	ds_read_b128 v[48:51], v21 offset:49552
	ds_read_b128 v[52:55], v21 offset:49568
	ds_read_b128 v[64:67], v21 offset:49584
	ds_read_b128 v[68:71], v21 offset:49600
	ds_read_b128 v[72:75], v21 offset:49616
	ds_read_b128 v[130:133], v21 offset:49632
	ds_read_b128 v[134:137], v21 offset:49648
	ds_read_b128 v[150:153], v21 offset:49664
	ds_read_b128 v[154:157], v21 offset:49680
	ds_read_b128 v[170:173], v21 offset:49696
	ds_read_b128 v[174:177], v21 offset:49712
	ds_read_b128 v[186:189], v21 offset:49728
	ds_read_b128 v[190:193], v21 offset:49744
	ds_read_b128 v[194:197], v21 offset:49760
	s_waitcnt lgkmcnt(14)
; #define WY_RDBLK(m_) do { _Pragma("unroll") for (int t_ = 0; t_ <= (m_); ++t_) LB[(m_) & 1][t_] = *(const LAS f32x4*)(lq + (m_) * WY_BS + 4 * t_); } while (0)
; __device__ __forceinline__ int wy_producer_task(const Ctx& c, int l, int tk, WyPre& P, unsigned* head) {
;     ...
; #pragma unroll
;         for (int m = 0; m < 16; ++m) {
;             if (m + 1 < 16) WY_RDBLK(m + 1);
;             __builtin_amdgcn_sched_barrier(0);
;             f32x4 pre = (f32x4){0.f, 0.f, 0.f, 0.f};
; #pragma unroll
;             for (int t = 0; t < m; ++t) pre = LB[m & 1][t] * own[t] + pre;
; #pragma unroll
;             for (int rr = 0; rr < 4; ++rr) {
;                 float acc = ((q4 == rr) ? own[m] : 0.f) - pre[rr];
;                 if (rr > 0) acc = fmaf(-LB[m & 1][m][rr], own[m], acc);
;                 const float x = quad_sum(acc);
;                 own[m] = (q4 == rr) ? x : own[m]; }
;             __builtin_amdgcn_sched_barrier(0);
	v_pk_fma_f32 v[38:39], v[18:19], v[40:41], 0 op_sel_hi:[0,1,0]
	v_pk_fma_f32 v[38:39], v[20:21], v[44:45], v[38:39] op_sel_hi:[0,1,1]
	v_pk_fma_f32 v[32:33], v[18:19], v[42:43], 0 op_sel_hi:[0,1,0]
	v_pk_fma_f32 v[38:39], v[16:17], v[56:57], v[38:39] op_sel_hi:[0,1,1]
	v_pk_fma_f32 v[32:33], v[20:21], v[46:47], v[32:33] op_sel_hi:[0,1,1]
	v_pk_fma_f32 v[38:39], v[22:23], v[60:61], v[38:39] op_sel_hi:[0,1,1]
	v_pk_fma_f32 v[32:33], v[16:17], v[58:59], v[32:33] op_sel_hi:[0,1,1]
	v_pk_fma_f32 v[38:39], v[14:15], v[78:79], v[38:39] op_sel_hi:[0,1,1]
	v_pk_fma_f32 v[32:33], v[22:23], v[62:63], v[32:33] op_sel_hi:[0,1,1]
	v_pk_fma_f32 v[38:39], v[24:25], v[126:127], v[38:39] op_sel_hi:[0,1,1]
	v_pk_fma_f32 v[32:33], v[14:15], v[80:81], v[32:33] op_sel_hi:[0,1,1]
	v_pk_fma_f32 v[38:39], v[12:13], v[138:139], v[38:39] op_sel_hi:[0,1,1]
	v_pk_fma_f32 v[32:33], v[24:25], v[128:129], v[32:33] op_sel_hi:[0,1,1]
	v_pk_fma_f32 v[38:39], v[26:27], v[142:143], v[38:39] op_sel_hi:[0,1,1]
	v_pk_fma_f32 v[32:33], v[12:13], v[140:141], v[32:33] op_sel_hi:[0,1,1]
	v_pk_fma_f32 v[38:39], v[10:11], v[146:147], v[38:39] op_sel_hi:[0,1,1]
	v_pk_fma_f32 v[32:33], v[26:27], v[144:145], v[32:33] op_sel_hi:[0,1,1]
	v_pk_fma_f32 v[38:39], v[28:29], v[158:159], v[38:39] op_sel_hi:[0,1,1]
	v_pk_fma_f32 v[32:33], v[10:11], v[148:149], v[32:33] op_sel_hi:[0,1,1]
	v_pk_fma_f32 v[38:39], v[162:163], v[8:9], v[38:39] op_sel_hi:[1,0,1]
	v_pk_fma_f32 v[32:33], v[28:29], v[160:161], v[32:33] op_sel_hi:[0,1,1]
	v_pk_fma_f32 v[38:39], v[166:167], v[30:31], v[38:39] op_sel_hi:[1,0,1]
	v_pk_fma_f32 v[32:33], v[164:165], v[8:9], v[32:33] op_sel_hi:[1,0,1]
	v_pk_fma_f32 v[38:39], v[178:179], v[6:7], v[38:39] op_sel_hi:[1,0,1]
	v_fma_f32 v9, v7, v236, -v38
	v_fma_f32 v11, v7, v237, -v39
	s_nop 0
	v_add_f32_dpp v9, v9, v9 quad_perm:[1,0,3,2] row_mask:0xf bank_mask:0xf bound_ctrl:1
	v_pk_fma_f32 v[32:33], v[168:169], v[30:31], v[32:33] op_sel_hi:[1,0,1]
	s_nop 0
	v_add_f32_dpp v9, v9, v9 quad_perm:[2,3,0,1] row_mask:0xf bank_mask:0xf bound_ctrl:1
	v_cndmask_b32_e64 v9, v7, v9, s[6:7]
	v_fma_f32 v11, -v183, v9, v11
	v_pk_fma_f32 v[32:33], v[180:181], v[6:7], v[32:33] op_sel_hi:[1,0,1]
	s_nop 0
	v_add_f32_dpp v11, v11, v11 quad_perm:[1,0,3,2] row_mask:0xf bank_mask:0xf bound_ctrl:1
	s_nop 1
	v_add_f32_dpp v11, v11, v11 quad_perm:[2,3,0,1] row_mask:0xf bank_mask:0xf bound_ctrl:1
	v_cndmask_b32_e32 v9, v9, v11, vcc
	v_fma_f32 v11, v7, v238, -v32
	v_fma_f32 v11, -v184, v9, v11
	v_fma_f32 v7, v7, v239, -v33
	s_nop 0
	v_add_f32_dpp v11, v11, v11 quad_perm:[1,0,3,2] row_mask:0xf bank_mask:0xf bound_ctrl:1
	s_nop 1
	v_add_f32_dpp v11, v11, v11 quad_perm:[2,3,0,1] row_mask:0xf bank_mask:0xf bound_ctrl:1
	v_cndmask_b32_e64 v9, v9, v11, s[2:3]
	v_fma_f32 v7, -v185, v9, v7
	s_nop 1
	v_add_f32_dpp v7, v7, v7 quad_perm:[1,0,3,2] row_mask:0xf bank_mask:0xf bound_ctrl:1
	s_nop 1
	v_add_f32_dpp v7, v7, v7 quad_perm:[2,3,0,1] row_mask:0xf bank_mask:0xf bound_ctrl:1
	v_cndmask_b32_e64 v32, v9, v7, s[4:5]
	ds_read_b128 v[38:41], v21 offset:50624
	ds_read_b128 v[42:45], v21 offset:50640
	ds_read_b128 v[56:59], v21 offset:50656
	ds_read_b128 v[60:63], v21 offset:50672
	ds_read_b128 v[76:79], v21 offset:50688
	ds_read_b128 v[126:129], v21 offset:50704
	ds_read_b128 v[138:141], v21 offset:50720
	ds_read_b128 v[142:145], v21 offset:50736
	ds_read_b128 v[146:149], v21 offset:50752
	ds_read_b128 v[158:161], v21 offset:50768
	ds_read_b128 v[162:165], v21 offset:50784
	ds_read_b128 v[166:169], v21 offset:50800
	ds_read_b128 v[178:181], v21 offset:50816
	ds_read_b128 v[182:185], v21 offset:50832
	ds_read_b128 v[198:201], v21 offset:50848
	ds_read_b128 v[202:205], v21 offset:50864
	v_pk_fma_f32 v[34:35], v[18:19], v[34:35], 0 op_sel_hi:[0,1,0]
	v_pk_fma_f32 v[36:37], v[18:19], v[36:37], 0 op_sel_hi:[0,1,0]
	s_waitcnt lgkmcnt(14)
	v_pk_fma_f32 v[34:35], v[20:21], v[48:49], v[34:35] op_sel_hi:[0,1,1]
	v_pk_fma_f32 v[36:37], v[20:21], v[50:51], v[36:37] op_sel_hi:[0,1,1]
	v_pk_fma_f32 v[34:35], v[16:17], v[52:53], v[34:35] op_sel_hi:[0,1,1]
	v_pk_fma_f32 v[36:37], v[16:17], v[54:55], v[36:37] op_sel_hi:[0,1,1]
	v_pk_fma_f32 v[34:35], v[22:23], v[64:65], v[34:35] op_sel_hi:[0,1,1]
	v_pk_fma_f32 v[36:37], v[22:23], v[66:67], v[36:37] op_sel_hi:[0,1,1]
	v_pk_fma_f32 v[34:35], v[14:15], v[68:69], v[34:35] op_sel_hi:[0,1,1]
	v_pk_fma_f32 v[36:37], v[14:15], v[70:71], v[36:37] op_sel_hi:[0,1,1]
	v_pk_fma_f32 v[34:35], v[24:25], v[72:73], v[34:35] op_sel_hi:[0,1,1]
	v_pk_fma_f32 v[36:37], v[24:25], v[74:75], v[36:37] op_sel_hi:[0,1,1]
	v_pk_fma_f32 v[34:35], v[12:13], v[130:131], v[34:35] op_sel_hi:[0,1,1]
	v_pk_fma_f32 v[36:37], v[12:13], v[132:133], v[36:37] op_sel_hi:[0,1,1]
	v_pk_fma_f32 v[34:35], v[26:27], v[134:135], v[34:35] op_sel_hi:[0,1,1]
	v_pk_fma_f32 v[36:37], v[26:27], v[136:137], v[36:37] op_sel_hi:[0,1,1]
	v_pk_fma_f32 v[34:35], v[10:11], v[150:151], v[34:35] op_sel_hi:[0,1,1]
	v_pk_fma_f32 v[36:37], v[10:11], v[152:153], v[36:37] op_sel_hi:[0,1,1]
	v_pk_fma_f32 v[34:35], v[28:29], v[154:155], v[34:35] op_sel_hi:[0,1,1]
	v_pk_fma_f32 v[36:37], v[28:29], v[156:157], v[36:37] op_sel_hi:[0,1,1]
	v_pk_fma_f32 v[34:35], v[8:9], v[170:171], v[34:35] op_sel_hi:[0,1,1]
	v_pk_fma_f32 v[36:37], v[8:9], v[172:173], v[36:37] op_sel_hi:[0,1,1]
	v_pk_fma_f32 v[34:35], v[174:175], v[30:31], v[34:35] op_sel_hi:[1,0,1]
	v_pk_fma_f32 v[36:37], v[176:177], v[30:31], v[36:37] op_sel_hi:[1,0,1]
	v_pk_fma_f32 v[34:35], v[186:187], v[6:7], v[34:35] op_sel_hi:[1,0,1]
	v_pk_fma_f32 v[36:37], v[188:189], v[6:7], v[36:37] op_sel_hi:[1,0,1]
	v_pk_fma_f32 v[34:35], v[190:191], v[32:33], v[34:35] op_sel_hi:[1,0,1]
	v_fma_f32 v7, v4, v236, -v34
	v_fma_f32 v9, v4, v237, -v35
	s_nop 0
	v_add_f32_dpp v7, v7, v7 quad_perm:[1,0,3,2] row_mask:0xf bank_mask:0xf bound_ctrl:1
	v_pk_fma_f32 v[36:37], v[192:193], v[32:33], v[36:37] op_sel_hi:[1,0,1]
	s_nop 0
	v_add_f32_dpp v7, v7, v7 quad_perm:[2,3,0,1] row_mask:0xf bank_mask:0xf bound_ctrl:1
	v_cndmask_b32_e64 v7, v4, v7, s[6:7]
	v_fma_f32 v9, -v195, v7, v9
	s_nop 1
	v_add_f32_dpp v9, v9, v9 quad_perm:[1,0,3,2] row_mask:0xf bank_mask:0xf bound_ctrl:1
	s_nop 1
	v_add_f32_dpp v9, v9, v9 quad_perm:[2,3,0,1] row_mask:0xf bank_mask:0xf bound_ctrl:1
	v_cndmask_b32_e32 v7, v7, v9, vcc
	v_fma_f32 v9, v4, v238, -v36
	v_fma_f32 v9, -v196, v7, v9
	v_fma_f32 v4, v4, v239, -v37
	s_nop 0
	v_add_f32_dpp v9, v9, v9 quad_perm:[1,0,3,2] row_mask:0xf bank_mask:0xf bound_ctrl:1
	s_nop 1
	v_add_f32_dpp v9, v9, v9 quad_perm:[2,3,0,1] row_mask:0xf bank_mask:0xf bound_ctrl:1
	v_cndmask_b32_e64 v7, v7, v9, s[2:3]
	v_fma_f32 v4, -v197, v7, v4
	s_nop 1
	v_add_f32_dpp v4, v4, v4 quad_perm:[1,0,3,2] row_mask:0xf bank_mask:0xf bound_ctrl:1
	s_nop 1
	v_add_f32_dpp v4, v4, v4 quad_perm:[2,3,0,1] row_mask:0xf bank_mask:0xf bound_ctrl:1
	v_cndmask_b32_e64 v4, v7, v4, s[4:5]
	v_pk_fma_f32 v[36:37], v[18:19], v[38:39], 0 op_sel_hi:[0,1,0]
	v_pk_fma_f32 v[36:37], v[20:21], v[42:43], v[36:37] op_sel_hi:[0,1,1]
	v_pk_fma_f32 v[34:35], v[18:19], v[40:41], 0 op_sel_hi:[0,1,0]
	s_waitcnt lgkmcnt(13)
; #define WY_RDBLK(m_) do { _Pragma("unroll") for (int t_ = 0; t_ <= (m_); ++t_) LB[(m_) & 1][t_] = *(const LAS f32x4*)(lq + (m_) * WY_BS + 4 * t_); } while (0)
; __device__ __forceinline__ int wy_producer_task(const Ctx& c, int l, int tk, WyPre& P, unsigned* head) {
;     ...
; #pragma unroll
;         for (int m = 0; m < 16; ++m) {
;             if (m + 1 < 16) WY_RDBLK(m + 1);
;             __builtin_amdgcn_sched_barrier(0);
;             f32x4 pre = (f32x4){0.f, 0.f, 0.f, 0.f};
; #pragma unroll
;             for (int t = 0; t < m; ++t) pre = LB[m & 1][t] * own[t] + pre;
; #pragma unroll
;             for (int rr = 0; rr < 4; ++rr) {
;                 float acc = ((q4 == rr) ? own[m] : 0.f) - pre[rr];
;                 if (rr > 0) acc = fmaf(-LB[m & 1][m][rr], own[m], acc);
;                 const float x = quad_sum(acc);
;                 own[m] = (q4 == rr) ? x : own[m]; }
;             __builtin_amdgcn_sched_barrier(0);
;         }
;     ...
;     }
;     if (wid < 4) { float* vo = (float*)(AWS + WS_VAL) + (size_t)tk * 4096 + 16 * wid + cc;
; #pragma unroll
;         for (int t = 0; t < 16; ++t) vo[(4 * t + q4) * 64] = own[t]; }
;     else {
; #pragma unroll
;         for (int t = 0; t < 16; ++t) KT[(4 * t + q4) * 65 + 16 * (wid - 4) + cc] = own[t]; }
	v_pk_fma_f32 v[36:37], v[16:17], v[56:57], v[36:37] op_sel_hi:[0,1,1]
	v_pk_fma_f32 v[34:35], v[20:21], v[44:45], v[34:35] op_sel_hi:[0,1,1]
	s_waitcnt lgkmcnt(12)
	v_pk_fma_f32 v[36:37], v[22:23], v[60:61], v[36:37] op_sel_hi:[0,1,1]
	v_pk_fma_f32 v[34:35], v[16:17], v[58:59], v[34:35] op_sel_hi:[0,1,1]
	s_waitcnt lgkmcnt(11)
	v_pk_fma_f32 v[36:37], v[14:15], v[76:77], v[36:37] op_sel_hi:[0,1,1]
	v_pk_fma_f32 v[34:35], v[22:23], v[62:63], v[34:35] op_sel_hi:[0,1,1]
	s_waitcnt lgkmcnt(10)
	v_pk_fma_f32 v[36:37], v[24:25], v[126:127], v[36:37] op_sel_hi:[0,1,1]
	v_pk_fma_f32 v[34:35], v[14:15], v[78:79], v[34:35] op_sel_hi:[0,1,1]
	s_waitcnt lgkmcnt(9)
	v_pk_fma_f32 v[36:37], v[12:13], v[138:139], v[36:37] op_sel_hi:[0,1,1]
	v_pk_fma_f32 v[34:35], v[24:25], v[128:129], v[34:35] op_sel_hi:[0,1,1]
	s_waitcnt lgkmcnt(8)
	v_pk_fma_f32 v[36:37], v[26:27], v[142:143], v[36:37] op_sel_hi:[0,1,1]
	v_pk_fma_f32 v[34:35], v[12:13], v[140:141], v[34:35] op_sel_hi:[0,1,1]
	s_waitcnt lgkmcnt(7)
	v_pk_fma_f32 v[36:37], v[10:11], v[146:147], v[36:37] op_sel_hi:[0,1,1]
	v_pk_fma_f32 v[34:35], v[26:27], v[144:145], v[34:35] op_sel_hi:[0,1,1]
	s_waitcnt lgkmcnt(6)
	v_pk_fma_f32 v[36:37], v[28:29], v[158:159], v[36:37] op_sel_hi:[0,1,1]
	v_pk_fma_f32 v[34:35], v[10:11], v[148:149], v[34:35] op_sel_hi:[0,1,1]
	s_waitcnt lgkmcnt(5)
	v_pk_fma_f32 v[36:37], v[8:9], v[162:163], v[36:37] op_sel_hi:[0,1,1]
	v_pk_fma_f32 v[34:35], v[28:29], v[160:161], v[34:35] op_sel_hi:[0,1,1]
	s_waitcnt lgkmcnt(4)
	v_pk_fma_f32 v[36:37], v[30:31], v[166:167], v[36:37] op_sel_hi:[0,1,1]
	v_pk_fma_f32 v[34:35], v[8:9], v[164:165], v[34:35] op_sel_hi:[0,1,1]
	s_waitcnt lgkmcnt(3)
	v_pk_fma_f32 v[36:37], v[178:179], v[6:7], v[36:37] op_sel_hi:[1,0,1]
	v_pk_fma_f32 v[34:35], v[30:31], v[168:169], v[34:35] op_sel_hi:[0,1,1]
	s_waitcnt lgkmcnt(2)
	v_pk_fma_f32 v[36:37], v[182:183], v[32:33], v[36:37] op_sel_hi:[1,0,1]
	v_pk_fma_f32 v[34:35], v[180:181], v[6:7], v[34:35] op_sel_hi:[1,0,1]
	s_waitcnt lgkmcnt(1)
	v_pk_fma_f32 v[36:37], v[198:199], v[4:5], v[36:37] op_sel_hi:[1,0,1]
	v_fma_f32 v7, v5, v236, -v36
	v_fma_f32 v9, v5, v237, -v37
	s_nop 0
	v_add_f32_dpp v7, v7, v7 quad_perm:[1,0,3,2] row_mask:0xf bank_mask:0xf bound_ctrl:1
	v_pk_fma_f32 v[34:35], v[184:185], v[32:33], v[34:35] op_sel_hi:[1,0,1]
	s_nop 0
	v_add_f32_dpp v7, v7, v7 quad_perm:[2,3,0,1] row_mask:0xf bank_mask:0xf bound_ctrl:1
	v_cndmask_b32_e64 v7, v5, v7, s[6:7]
	s_waitcnt lgkmcnt(0)
	v_fma_f32 v9, -v203, v7, v9
	v_pk_fma_f32 v[34:35], v[200:201], v[4:5], v[34:35] op_sel_hi:[1,0,1]
	s_nop 0
	v_add_f32_dpp v9, v9, v9 quad_perm:[1,0,3,2] row_mask:0xf bank_mask:0xf bound_ctrl:1
	s_nop 1
	v_add_f32_dpp v9, v9, v9 quad_perm:[2,3,0,1] row_mask:0xf bank_mask:0xf bound_ctrl:1
	v_cndmask_b32_e32 v7, v7, v9, vcc
	v_fma_f32 v9, v5, v238, -v34
	v_fma_f32 v9, -v204, v7, v9
	v_fma_f32 v5, v5, v239, -v35
	s_nop 0
	v_add_f32_dpp v9, v9, v9 quad_perm:[1,0,3,2] row_mask:0xf bank_mask:0xf bound_ctrl:1
	s_nop 1
	v_add_f32_dpp v9, v9, v9 quad_perm:[2,3,0,1] row_mask:0xf bank_mask:0xf bound_ctrl:1
	v_cndmask_b32_e64 v7, v7, v9, s[2:3]
	v_fma_f32 v5, -v205, v7, v5
	s_nop 1
	v_add_f32_dpp v5, v5, v5 quad_perm:[1,0,3,2] row_mask:0xf bank_mask:0xf bound_ctrl:1
	s_nop 1
	v_add_f32_dpp v5, v5, v5 quad_perm:[2,3,0,1] row_mask:0xf bank_mask:0xf bound_ctrl:1
	v_cndmask_b32_e64 v5, v7, v5, s[4:5]
	s_mov_b32 s2, 0x5040100
	s_waitcnt vmcnt(12)
	v_perm_b32 v114, v206, v207, s2
	v_perm_b32 v89, v208, v209, s2
	v_perm_b32 v115, v210, v211, s2
	v_perm_b32 v116, v212, v213, s2
	v_perm_b32 v117, v214, v215, s2
	v_perm_b32 v119, v216, v217, s2
	v_perm_b32 v118, v218, v219, s2
	v_perm_b32 v120, v230, v231, s2
	v_perm_b32 v121, v232, v233, s2
	v_perm_b32 v122, v234, v235, s2
	s_and_b64 vcc, exec, s[40:41]
	s_mov_b64 s[2:3], -1
	s_cbranch_vccnz .LBB0_1089
	ds_write_b32 v3, v18 offset:55552
	ds_write_b32 v3, v20 offset:56592
	ds_write_b32 v3, v16 offset:57632
	ds_write_b32 v3, v22 offset:58672
	ds_write_b32 v3, v14 offset:59712
	ds_write_b32 v3, v24 offset:60752
	ds_write_b32 v3, v12 offset:61792
	ds_write_b32 v3, v26 offset:62832
	ds_write_b32 v3, v10 offset:63872
	ds_write_b32 v3, v28 offset:64912
	v_add_u32_e32 v3, 0xda00, v3
	s_mov_b64 s[2:3], 0
	ds_write_b32 v3, v8 offset:10144
	ds_write_b32 v3, v30 offset:11184
	ds_write_b32 v3, v6 offset:12224
	ds_write_b32 v3, v32 offset:13264
	ds_write_b32 v3, v4 offset:14304
	ds_write_b32 v3, v5 offset:15344
